# v24 + P5/P6 EpiGate epilogues rewritten: gate/tmp loads issued ahead (ring), saddr addressing, counted vmcnt
# speedup vs baseline: 1.0052x; 1.0002x over previous
.LBB0_534:
	v_lshl_add_u32 v148, s18, 8, v1
	v_lshl_or_b32 v146, s41, 8, v151
	v_readlane_b32 s20, v245, 17
	v_readlane_b32 s21, v245, 18
	v_lshlrev_b32_e32 v147, 1, v146
	v_lshl_add_u32 v149, v148, 13, v147
	v_lshl_add_u32 v155, v148, 12, v147
	s_andn2_b64 vcc, exec, s[4:5]
	s_mov_b64 s[4:5], -1
	v_add_u32_e32 v238, 0x20000, v149
	v_add_u32_e32 v239, 0x40000, v149
	v_add_u32_e32 v240, 0x60000, v149
	v_add_u32_e32 v241, 0x100000, v149
	v_add_u32_e32 v242, 0x120000, v149
	v_add_u32_e32 v243, 0x140000, v149
	v_add_u32_e32 v244, 0x160000, v149
	global_load_dwordx4 v[156:159], v149, s[20:21]
	global_load_dwordx4 v[160:163], v149, s[20:21] offset:256
	global_load_dwordx4 v[164:167], v238, s[20:21]
	global_load_dwordx4 v[168:171], v238, s[20:21] offset:256
	global_load_dwordx4 v[172:175], v239, s[20:21]
	global_load_dwordx4 v[176:179], v239, s[20:21] offset:256
	global_load_dwordx4 v[180:183], v240, s[20:21]
	global_load_dwordx4 v[184:187], v240, s[20:21] offset:256
	global_load_dwordx4 v[188:191], v241, s[20:21]
	global_load_dwordx4 v[192:195], v241, s[20:21] offset:256
	global_load_dwordx4 v[196:199], v242, s[20:21]
	global_load_dwordx4 v[200:203], v242, s[20:21] offset:256
	global_load_dwordx4 v[204:207], v243, s[20:21]
	global_load_dwordx4 v[208:211], v243, s[20:21] offset:256
	global_load_dwordx4 v[212:215], v244, s[20:21]
	global_load_dwordx4 v[216:219], v244, s[20:21] offset:256
	s_waitcnt vmcnt(15)
	v_lshlrev_b32_e32 v220, 16, v156
	v_and_b32_e32 v221, 0xffff0000, v156
	v_lshlrev_b32_e32 v156, 16, v157
	v_and_b32_e32 v157, 0xffff0000, v157
	v_lshlrev_b32_e32 v222, 16, v158
	v_and_b32_e32 v223, 0xffff0000, v158
	v_lshlrev_b32_e32 v158, 16, v159
	v_and_b32_e32 v159, 0xffff0000, v159
	v_pk_mul_f32 v[126:127], v[126:127], v[220:221]
	v_pk_mul_f32 v[128:129], v[128:129], v[156:157]
	v_pk_mul_f32 v[122:123], v[122:123], v[222:223]
	v_pk_mul_f32 v[124:125], v[124:125], v[158:159]
	v_cvt_pk_bf16_f32 v224, v126, v127
	v_cvt_pk_bf16_f32 v225, v128, v129
	v_cvt_pk_bf16_f32 v226, v122, v123
	v_cvt_pk_bf16_f32 v227, v124, v125
	global_store_dwordx4 v155, v[224:227], s[2:3]
	s_waitcnt vmcnt(15)
	v_lshlrev_b32_e32 v220, 16, v160
	v_and_b32_e32 v221, 0xffff0000, v160
	v_lshlrev_b32_e32 v160, 16, v161
	v_and_b32_e32 v161, 0xffff0000, v161
	v_lshlrev_b32_e32 v222, 16, v162
	v_and_b32_e32 v223, 0xffff0000, v162
	v_lshlrev_b32_e32 v162, 16, v163
	v_and_b32_e32 v163, 0xffff0000, v163
	v_pk_mul_f32 v[118:119], v[118:119], v[220:221]
	v_pk_mul_f32 v[120:121], v[120:121], v[160:161]
	v_pk_mul_f32 v[114:115], v[114:115], v[222:223]
	v_pk_mul_f32 v[116:117], v[116:117], v[162:163]
	v_cvt_pk_bf16_f32 v228, v118, v119
	v_cvt_pk_bf16_f32 v229, v120, v121
	v_cvt_pk_bf16_f32 v230, v114, v115
	v_cvt_pk_bf16_f32 v231, v116, v117
	global_store_dwordx4 v155, v[228:231], s[2:3] offset:256
	v_add_u32_e32 v233, 0x10000, v155
	s_waitcnt vmcnt(15)
	v_lshlrev_b32_e32 v220, 16, v164
	v_and_b32_e32 v221, 0xffff0000, v164
	v_lshlrev_b32_e32 v164, 16, v165
	v_and_b32_e32 v165, 0xffff0000, v165
	v_lshlrev_b32_e32 v222, 16, v166
	v_and_b32_e32 v223, 0xffff0000, v166
	v_lshlrev_b32_e32 v166, 16, v167
	v_and_b32_e32 v167, 0xffff0000, v167
	v_pk_mul_f32 v[110:111], v[110:111], v[220:221]
	v_pk_mul_f32 v[112:113], v[112:113], v[164:165]
	v_pk_mul_f32 v[106:107], v[106:107], v[222:223]
	v_pk_mul_f32 v[108:109], v[108:109], v[166:167]
	v_cvt_pk_bf16_f32 v224, v110, v111
	v_cvt_pk_bf16_f32 v225, v112, v113
	v_cvt_pk_bf16_f32 v226, v106, v107
	v_cvt_pk_bf16_f32 v227, v108, v109
	global_store_dwordx4 v233, v[224:227], s[2:3]
	s_waitcnt vmcnt(15)
	v_lshlrev_b32_e32 v220, 16, v168
	v_and_b32_e32 v221, 0xffff0000, v168
	v_lshlrev_b32_e32 v168, 16, v169
	v_and_b32_e32 v169, 0xffff0000, v169
	v_lshlrev_b32_e32 v222, 16, v170
	v_and_b32_e32 v223, 0xffff0000, v170
	v_lshlrev_b32_e32 v170, 16, v171
	v_and_b32_e32 v171, 0xffff0000, v171
	v_pk_mul_f32 v[102:103], v[102:103], v[220:221]
	v_pk_mul_f32 v[104:105], v[104:105], v[168:169]
	v_pk_mul_f32 v[98:99], v[98:99], v[222:223]
	v_pk_mul_f32 v[100:101], v[100:101], v[170:171]
	v_cvt_pk_bf16_f32 v228, v102, v103
	v_cvt_pk_bf16_f32 v229, v104, v105
	v_cvt_pk_bf16_f32 v230, v98, v99
	v_cvt_pk_bf16_f32 v231, v100, v101
	global_store_dwordx4 v233, v[228:231], s[2:3] offset:256
	v_add_u32_e32 v232, 0x20000, v155
	s_waitcnt vmcnt(15)
	v_lshlrev_b32_e32 v220, 16, v172
	v_and_b32_e32 v221, 0xffff0000, v172
	v_lshlrev_b32_e32 v172, 16, v173
	v_and_b32_e32 v173, 0xffff0000, v173
	v_lshlrev_b32_e32 v222, 16, v174
	v_and_b32_e32 v223, 0xffff0000, v174
	v_lshlrev_b32_e32 v174, 16, v175
	v_and_b32_e32 v175, 0xffff0000, v175
	v_pk_mul_f32 v[94:95], v[94:95], v[220:221]
	v_pk_mul_f32 v[96:97], v[96:97], v[172:173]
	v_pk_mul_f32 v[90:91], v[90:91], v[222:223]
	v_pk_mul_f32 v[92:93], v[92:93], v[174:175]
	v_cvt_pk_bf16_f32 v224, v94, v95
	v_cvt_pk_bf16_f32 v225, v96, v97
	v_cvt_pk_bf16_f32 v226, v90, v91
	v_cvt_pk_bf16_f32 v227, v92, v93
	global_store_dwordx4 v232, v[224:227], s[2:3]
	s_waitcnt vmcnt(15)
	v_lshlrev_b32_e32 v220, 16, v176
	v_and_b32_e32 v221, 0xffff0000, v176
	v_lshlrev_b32_e32 v176, 16, v177
	v_and_b32_e32 v177, 0xffff0000, v177
	v_lshlrev_b32_e32 v222, 16, v178
	v_and_b32_e32 v223, 0xffff0000, v178
	v_lshlrev_b32_e32 v178, 16, v179
	v_and_b32_e32 v179, 0xffff0000, v179
	v_pk_mul_f32 v[86:87], v[86:87], v[220:221]
	v_pk_mul_f32 v[88:89], v[88:89], v[176:177]
	v_pk_mul_f32 v[82:83], v[82:83], v[222:223]
	v_pk_mul_f32 v[84:85], v[84:85], v[178:179]
	v_cvt_pk_bf16_f32 v228, v86, v87
	v_cvt_pk_bf16_f32 v229, v88, v89
	v_cvt_pk_bf16_f32 v230, v82, v83
	v_cvt_pk_bf16_f32 v231, v84, v85
	global_store_dwordx4 v232, v[228:231], s[2:3] offset:256
	v_add_u32_e32 v233, 0x30000, v155
	s_waitcnt vmcnt(15)
	v_lshlrev_b32_e32 v220, 16, v180
	v_and_b32_e32 v221, 0xffff0000, v180
	v_lshlrev_b32_e32 v180, 16, v181
	v_and_b32_e32 v181, 0xffff0000, v181
	v_lshlrev_b32_e32 v222, 16, v182
	v_and_b32_e32 v223, 0xffff0000, v182
	v_lshlrev_b32_e32 v182, 16, v183
	v_and_b32_e32 v183, 0xffff0000, v183
	v_pk_mul_f32 v[78:79], v[78:79], v[220:221]
	v_pk_mul_f32 v[80:81], v[80:81], v[180:181]
	v_pk_mul_f32 v[74:75], v[74:75], v[222:223]
	v_pk_mul_f32 v[76:77], v[76:77], v[182:183]
	v_cvt_pk_bf16_f32 v224, v78, v79
	v_cvt_pk_bf16_f32 v225, v80, v81
	v_cvt_pk_bf16_f32 v226, v74, v75
	v_cvt_pk_bf16_f32 v227, v76, v77
	global_store_dwordx4 v233, v[224:227], s[2:3]
	s_waitcnt vmcnt(15)
	v_lshlrev_b32_e32 v220, 16, v184
	v_and_b32_e32 v221, 0xffff0000, v184
	v_lshlrev_b32_e32 v184, 16, v185
	v_and_b32_e32 v185, 0xffff0000, v185
	v_lshlrev_b32_e32 v222, 16, v186
	v_and_b32_e32 v223, 0xffff0000, v186
	v_lshlrev_b32_e32 v186, 16, v187
	v_and_b32_e32 v187, 0xffff0000, v187
	v_pk_mul_f32 v[70:71], v[70:71], v[220:221]
	v_pk_mul_f32 v[72:73], v[72:73], v[184:185]
	v_pk_mul_f32 v[66:67], v[66:67], v[222:223]
	v_pk_mul_f32 v[68:69], v[68:69], v[186:187]
	v_cvt_pk_bf16_f32 v228, v70, v71
	v_cvt_pk_bf16_f32 v229, v72, v73
	v_cvt_pk_bf16_f32 v230, v66, v67
	v_cvt_pk_bf16_f32 v231, v68, v69
	global_store_dwordx4 v233, v[228:231], s[2:3] offset:256
	v_add_u32_e32 v232, 0x80000, v155
	s_waitcnt vmcnt(15)
	v_lshlrev_b32_e32 v220, 16, v188
	v_and_b32_e32 v221, 0xffff0000, v188
	v_lshlrev_b32_e32 v188, 16, v189
	v_and_b32_e32 v189, 0xffff0000, v189
	v_lshlrev_b32_e32 v222, 16, v190
	v_and_b32_e32 v223, 0xffff0000, v190
	v_lshlrev_b32_e32 v190, 16, v191
	v_and_b32_e32 v191, 0xffff0000, v191
	v_pk_mul_f32 v[62:63], v[62:63], v[220:221]
	v_pk_mul_f32 v[64:65], v[64:65], v[188:189]
	v_pk_mul_f32 v[58:59], v[58:59], v[222:223]
	v_pk_mul_f32 v[60:61], v[60:61], v[190:191]
	v_cvt_pk_bf16_f32 v224, v62, v63
	v_cvt_pk_bf16_f32 v225, v64, v65
	v_cvt_pk_bf16_f32 v226, v58, v59
	v_cvt_pk_bf16_f32 v227, v60, v61
	global_store_dwordx4 v232, v[224:227], s[2:3]
	s_waitcnt vmcnt(15)
	v_lshlrev_b32_e32 v220, 16, v192
	v_and_b32_e32 v221, 0xffff0000, v192
	v_lshlrev_b32_e32 v192, 16, v193
	v_and_b32_e32 v193, 0xffff0000, v193
	v_lshlrev_b32_e32 v222, 16, v194
	v_and_b32_e32 v223, 0xffff0000, v194
	v_lshlrev_b32_e32 v194, 16, v195
	v_and_b32_e32 v195, 0xffff0000, v195
	v_pk_mul_f32 v[54:55], v[54:55], v[220:221]
	v_pk_mul_f32 v[56:57], v[56:57], v[192:193]
	v_pk_mul_f32 v[50:51], v[50:51], v[222:223]
	v_pk_mul_f32 v[52:53], v[52:53], v[194:195]
	v_cvt_pk_bf16_f32 v228, v54, v55
	v_cvt_pk_bf16_f32 v229, v56, v57
	v_cvt_pk_bf16_f32 v230, v50, v51
	v_cvt_pk_bf16_f32 v231, v52, v53
	global_store_dwordx4 v232, v[228:231], s[2:3] offset:256
	v_add_u32_e32 v233, 0x90000, v155
	s_waitcnt vmcnt(15)
	v_lshlrev_b32_e32 v220, 16, v196
	v_and_b32_e32 v221, 0xffff0000, v196
	v_lshlrev_b32_e32 v196, 16, v197
	v_and_b32_e32 v197, 0xffff0000, v197
	v_lshlrev_b32_e32 v222, 16, v198
	v_and_b32_e32 v223, 0xffff0000, v198
	v_lshlrev_b32_e32 v198, 16, v199
	v_and_b32_e32 v199, 0xffff0000, v199
	v_pk_mul_f32 v[46:47], v[46:47], v[220:221]
	v_pk_mul_f32 v[48:49], v[48:49], v[196:197]
	v_pk_mul_f32 v[42:43], v[42:43], v[222:223]
	v_pk_mul_f32 v[44:45], v[44:45], v[198:199]
	v_cvt_pk_bf16_f32 v224, v46, v47
	v_cvt_pk_bf16_f32 v225, v48, v49
	v_cvt_pk_bf16_f32 v226, v42, v43
	v_cvt_pk_bf16_f32 v227, v44, v45
	global_store_dwordx4 v233, v[224:227], s[2:3]
	s_waitcnt vmcnt(15)
	v_lshlrev_b32_e32 v220, 16, v200
	v_and_b32_e32 v221, 0xffff0000, v200
	v_lshlrev_b32_e32 v200, 16, v201
	v_and_b32_e32 v201, 0xffff0000, v201
	v_lshlrev_b32_e32 v222, 16, v202
	v_and_b32_e32 v223, 0xffff0000, v202
	v_lshlrev_b32_e32 v202, 16, v203
	v_and_b32_e32 v203, 0xffff0000, v203
	v_pk_mul_f32 v[38:39], v[38:39], v[220:221]
	v_pk_mul_f32 v[40:41], v[40:41], v[200:201]
	v_pk_mul_f32 v[34:35], v[34:35], v[222:223]
	v_pk_mul_f32 v[36:37], v[36:37], v[202:203]
	v_cvt_pk_bf16_f32 v228, v38, v39
	v_cvt_pk_bf16_f32 v229, v40, v41
	v_cvt_pk_bf16_f32 v230, v34, v35
	v_cvt_pk_bf16_f32 v231, v36, v37
	global_store_dwordx4 v233, v[228:231], s[2:3] offset:256
	v_add_u32_e32 v232, 0xa0000, v155
	s_waitcnt vmcnt(15)
	v_lshlrev_b32_e32 v220, 16, v204
	v_and_b32_e32 v221, 0xffff0000, v204
	v_lshlrev_b32_e32 v204, 16, v205
	v_and_b32_e32 v205, 0xffff0000, v205
	v_lshlrev_b32_e32 v222, 16, v206
	v_and_b32_e32 v223, 0xffff0000, v206
	v_lshlrev_b32_e32 v206, 16, v207
	v_and_b32_e32 v207, 0xffff0000, v207
	v_pk_mul_f32 v[30:31], v[30:31], v[220:221]
	v_pk_mul_f32 v[32:33], v[32:33], v[204:205]
	v_pk_mul_f32 v[26:27], v[26:27], v[222:223]
	v_pk_mul_f32 v[28:29], v[28:29], v[206:207]
	v_cvt_pk_bf16_f32 v224, v30, v31
	v_cvt_pk_bf16_f32 v225, v32, v33
	v_cvt_pk_bf16_f32 v226, v26, v27
	v_cvt_pk_bf16_f32 v227, v28, v29
	global_store_dwordx4 v232, v[224:227], s[2:3]
	s_waitcnt vmcnt(15)
	v_lshlrev_b32_e32 v220, 16, v208
	v_and_b32_e32 v221, 0xffff0000, v208
	v_lshlrev_b32_e32 v208, 16, v209
	v_and_b32_e32 v209, 0xffff0000, v209
	v_lshlrev_b32_e32 v222, 16, v210
	v_and_b32_e32 v223, 0xffff0000, v210
	v_lshlrev_b32_e32 v210, 16, v211
	v_and_b32_e32 v211, 0xffff0000, v211
	v_pk_mul_f32 v[22:23], v[22:23], v[220:221]
	v_pk_mul_f32 v[24:25], v[24:25], v[208:209]
	v_pk_mul_f32 v[18:19], v[18:19], v[222:223]
	v_pk_mul_f32 v[20:21], v[20:21], v[210:211]
	v_cvt_pk_bf16_f32 v228, v22, v23
	v_cvt_pk_bf16_f32 v229, v24, v25
	v_cvt_pk_bf16_f32 v230, v18, v19
	v_cvt_pk_bf16_f32 v231, v20, v21
	global_store_dwordx4 v232, v[228:231], s[2:3] offset:256
	v_add_u32_e32 v233, 0xb0000, v155
	s_waitcnt vmcnt(15)
	v_lshlrev_b32_e32 v220, 16, v212
	v_and_b32_e32 v221, 0xffff0000, v212
	v_lshlrev_b32_e32 v212, 16, v213
	v_and_b32_e32 v213, 0xffff0000, v213
	v_lshlrev_b32_e32 v222, 16, v214
	v_and_b32_e32 v223, 0xffff0000, v214
	v_lshlrev_b32_e32 v214, 16, v215
	v_and_b32_e32 v215, 0xffff0000, v215
	v_pk_mul_f32 v[14:15], v[14:15], v[220:221]
	v_pk_mul_f32 v[16:17], v[16:17], v[212:213]
	v_pk_mul_f32 v[10:11], v[10:11], v[222:223]
	v_pk_mul_f32 v[12:13], v[12:13], v[214:215]
	v_cvt_pk_bf16_f32 v224, v14, v15
	v_cvt_pk_bf16_f32 v225, v16, v17
	v_cvt_pk_bf16_f32 v226, v10, v11
	v_cvt_pk_bf16_f32 v227, v12, v13
	global_store_dwordx4 v233, v[224:227], s[2:3]
	s_waitcnt vmcnt(15)
	v_lshlrev_b32_e32 v220, 16, v216
	v_and_b32_e32 v221, 0xffff0000, v216
	v_lshlrev_b32_e32 v216, 16, v217
	v_and_b32_e32 v217, 0xffff0000, v217
	v_lshlrev_b32_e32 v222, 16, v218
	v_and_b32_e32 v223, 0xffff0000, v218
	v_lshlrev_b32_e32 v218, 16, v219
	v_and_b32_e32 v219, 0xffff0000, v219
	v_pk_mul_f32 v[6:7], v[6:7], v[220:221]
	v_pk_mul_f32 v[8:9], v[8:9], v[216:217]
	v_pk_mul_f32 v[2:3], v[2:3], v[222:223]
	v_pk_mul_f32 v[4:5], v[4:5], v[218:219]
	v_cvt_pk_bf16_f32 v228, v6, v7
	v_cvt_pk_bf16_f32 v229, v8, v9
	v_cvt_pk_bf16_f32 v230, v2, v3
	v_cvt_pk_bf16_f32 v231, v4, v5
	global_store_dwordx4 v233, v[228:231], s[2:3] offset:256
	s_cbranch_vccnz .LBB0_523
	s_andn2_b64 vcc, exec, s[0:1]
	s_cbranch_vccnz .LBB0_522
	s_barrier
	s_branch .LBB0_522

.LBB0_559:
	v_lshl_add_u32 v150, s22, 8, v1
	v_lshl_or_b32 v151, s47, 8, v153
	v_readlane_b32 s26, v245, 17
	v_readlane_b32 s27, v245, 18
	v_readlane_b32 s24, v245, 14
	v_readlane_b32 s25, v245, 15
	v_lshlrev_b32_e32 v151, 1, v151
	v_lshl_add_u32 v157, v150, 13, v151
	v_lshl_add_u32 v254, v150, 12, v151
	v_add_u32_e32 v157, 0x1000, v157
	s_andn2_b64 vcc, exec, s[4:5]
	s_mov_b64 s[4:5], -1
	global_load_dwordx4 v[158:161], v157, s[26:27]
	global_load_dwordx4 v[162:165], v254, s[6:7]
	global_load_dwordx4 v[166:169], v157, s[26:27] offset:256
	global_load_dwordx4 v[170:173], v254, s[6:7] offset:256
	v_add_u32_e32 v242, 0x20000, v157
	v_add_u32_e32 v243, 0x10000, v254
	global_load_dwordx4 v[174:177], v242, s[26:27]
	global_load_dwordx4 v[178:181], v243, s[6:7]
	global_load_dwordx4 v[182:185], v242, s[26:27] offset:256
	global_load_dwordx4 v[186:189], v243, s[6:7] offset:256
	v_add_u32_e32 v242, 0x40000, v157
	v_add_u32_e32 v243, 0x20000, v254
	global_load_dwordx4 v[190:193], v242, s[26:27]
	global_load_dwordx4 v[194:197], v243, s[6:7]
	global_load_dwordx4 v[198:201], v242, s[26:27] offset:256
	global_load_dwordx4 v[202:205], v243, s[6:7] offset:256
	v_add_u32_e32 v242, 0x60000, v157
	v_add_u32_e32 v243, 0x30000, v254
	global_load_dwordx4 v[206:209], v242, s[26:27]
	global_load_dwordx4 v[210:213], v243, s[6:7]
	global_load_dwordx4 v[214:217], v242, s[26:27] offset:256
	global_load_dwordx4 v[218:221], v243, s[6:7] offset:256
	v_add_u32_e32 v242, 0x100000, v157
	v_add_u32_e32 v243, 0x80000, v254
	global_load_dwordx4 v[222:225], v242, s[26:27]
	global_load_dwordx4 v[226:229], v243, s[6:7]
	global_load_dwordx4 v[230:233], v242, s[26:27] offset:256
	global_load_dwordx4 v[234:237], v243, s[6:7] offset:256
	s_waitcnt vmcnt(18)
	v_lshlrev_b32_e32 v246, 16, v158
	v_and_b32_e32 v247, 0xffff0000, v158
	v_lshlrev_b32_e32 v158, 16, v159
	v_and_b32_e32 v159, 0xffff0000, v159
	v_lshlrev_b32_e32 v248, 16, v160
	v_and_b32_e32 v249, 0xffff0000, v160
	v_lshlrev_b32_e32 v160, 16, v161
	v_and_b32_e32 v161, 0xffff0000, v161
	v_lshlrev_b32_e32 v250, 16, v162
	v_and_b32_e32 v251, 0xffff0000, v162
	v_lshlrev_b32_e32 v162, 16, v163
	v_and_b32_e32 v163, 0xffff0000, v163
	v_lshlrev_b32_e32 v252, 16, v164
	v_and_b32_e32 v253, 0xffff0000, v164
	v_lshlrev_b32_e32 v164, 16, v165
	v_and_b32_e32 v165, 0xffff0000, v165
	v_pk_fma_f32 v[126:127], v[126:127], v[246:247], v[250:251]
	v_pk_fma_f32 v[128:129], v[128:129], v[158:159], v[162:163]
	v_pk_fma_f32 v[122:123], v[122:123], v[248:249], v[252:253]
	v_pk_fma_f32 v[124:125], v[124:125], v[160:161], v[164:165]
	v_cvt_pk_bf16_f32 v238, v126, v127
	v_cvt_pk_bf16_f32 v239, v128, v129
	v_cvt_pk_bf16_f32 v240, v122, v123
	v_cvt_pk_bf16_f32 v241, v124, v125
	global_store_dwordx4 v254, v[238:241], s[24:25]
	s_waitcnt vmcnt(17)
	v_lshlrev_b32_e32 v246, 16, v166
	v_and_b32_e32 v247, 0xffff0000, v166
	v_lshlrev_b32_e32 v166, 16, v167
	v_and_b32_e32 v167, 0xffff0000, v167
	v_lshlrev_b32_e32 v248, 16, v168
	v_and_b32_e32 v249, 0xffff0000, v168
	v_lshlrev_b32_e32 v168, 16, v169
	v_and_b32_e32 v169, 0xffff0000, v169
	v_lshlrev_b32_e32 v250, 16, v170
	v_and_b32_e32 v251, 0xffff0000, v170
	v_lshlrev_b32_e32 v170, 16, v171
	v_and_b32_e32 v171, 0xffff0000, v171
	v_lshlrev_b32_e32 v252, 16, v172
	v_and_b32_e32 v253, 0xffff0000, v172
	v_lshlrev_b32_e32 v172, 16, v173
	v_and_b32_e32 v173, 0xffff0000, v173
	v_pk_fma_f32 v[118:119], v[118:119], v[246:247], v[250:251]
	v_pk_fma_f32 v[120:121], v[120:121], v[166:167], v[170:171]
	v_pk_fma_f32 v[114:115], v[114:115], v[248:249], v[252:253]
	v_pk_fma_f32 v[116:117], v[116:117], v[168:169], v[172:173]
	v_cvt_pk_bf16_f32 v146, v118, v119
	v_cvt_pk_bf16_f32 v147, v120, v121
	v_cvt_pk_bf16_f32 v148, v114, v115
	v_cvt_pk_bf16_f32 v149, v116, v117
	global_store_dwordx4 v254, v[146:149], s[24:25] offset:256
	v_add_u32_e32 v242, 0x120000, v157
	v_add_u32_e32 v243, 0x90000, v254
	global_load_dwordx4 v[158:161], v242, s[26:27]
	global_load_dwordx4 v[162:165], v243, s[6:7]
	global_load_dwordx4 v[166:169], v242, s[26:27] offset:256
	global_load_dwordx4 v[170:173], v243, s[6:7] offset:256
	v_add_u32_e32 v244, 0x10000, v254
	s_waitcnt vmcnt(20)
	v_lshlrev_b32_e32 v246, 16, v174
	v_and_b32_e32 v247, 0xffff0000, v174
	v_lshlrev_b32_e32 v174, 16, v175
	v_and_b32_e32 v175, 0xffff0000, v175
	v_lshlrev_b32_e32 v248, 16, v176
	v_and_b32_e32 v249, 0xffff0000, v176
	v_lshlrev_b32_e32 v176, 16, v177
	v_and_b32_e32 v177, 0xffff0000, v177
	v_lshlrev_b32_e32 v250, 16, v178
	v_and_b32_e32 v251, 0xffff0000, v178
	v_lshlrev_b32_e32 v178, 16, v179
	v_and_b32_e32 v179, 0xffff0000, v179
	v_lshlrev_b32_e32 v252, 16, v180
	v_and_b32_e32 v253, 0xffff0000, v180
	v_lshlrev_b32_e32 v180, 16, v181
	v_and_b32_e32 v181, 0xffff0000, v181
	v_pk_fma_f32 v[110:111], v[110:111], v[246:247], v[250:251]
	v_pk_fma_f32 v[112:113], v[112:113], v[174:175], v[178:179]
	v_pk_fma_f32 v[106:107], v[106:107], v[248:249], v[252:253]
	v_pk_fma_f32 v[108:109], v[108:109], v[176:177], v[180:181]
	v_cvt_pk_bf16_f32 v238, v110, v111
	v_cvt_pk_bf16_f32 v239, v112, v113
	v_cvt_pk_bf16_f32 v240, v106, v107
	v_cvt_pk_bf16_f32 v241, v108, v109
	global_store_dwordx4 v244, v[238:241], s[24:25]
	s_waitcnt vmcnt(19)
	v_lshlrev_b32_e32 v246, 16, v182
	v_and_b32_e32 v247, 0xffff0000, v182
	v_lshlrev_b32_e32 v182, 16, v183
	v_and_b32_e32 v183, 0xffff0000, v183
	v_lshlrev_b32_e32 v248, 16, v184
	v_and_b32_e32 v249, 0xffff0000, v184
	v_lshlrev_b32_e32 v184, 16, v185
	v_and_b32_e32 v185, 0xffff0000, v185
	v_lshlrev_b32_e32 v250, 16, v186
	v_and_b32_e32 v251, 0xffff0000, v186
	v_lshlrev_b32_e32 v186, 16, v187
	v_and_b32_e32 v187, 0xffff0000, v187
	v_lshlrev_b32_e32 v252, 16, v188
	v_and_b32_e32 v253, 0xffff0000, v188
	v_lshlrev_b32_e32 v188, 16, v189
	v_and_b32_e32 v189, 0xffff0000, v189
	v_pk_fma_f32 v[102:103], v[102:103], v[246:247], v[250:251]
	v_pk_fma_f32 v[104:105], v[104:105], v[182:183], v[186:187]
	v_pk_fma_f32 v[98:99], v[98:99], v[248:249], v[252:253]
	v_pk_fma_f32 v[100:101], v[100:101], v[184:185], v[188:189]
	v_cvt_pk_bf16_f32 v146, v102, v103
	v_cvt_pk_bf16_f32 v147, v104, v105
	v_cvt_pk_bf16_f32 v148, v98, v99
	v_cvt_pk_bf16_f32 v149, v100, v101
	global_store_dwordx4 v244, v[146:149], s[24:25] offset:256
	v_add_u32_e32 v242, 0x140000, v157
	v_add_u32_e32 v243, 0xa0000, v254
	global_load_dwordx4 v[174:177], v242, s[26:27]
	global_load_dwordx4 v[178:181], v243, s[6:7]
	global_load_dwordx4 v[182:185], v242, s[26:27] offset:256
	global_load_dwordx4 v[186:189], v243, s[6:7] offset:256
	v_add_u32_e32 v244, 0x20000, v254
	s_waitcnt vmcnt(22)
	v_lshlrev_b32_e32 v246, 16, v190
	v_and_b32_e32 v247, 0xffff0000, v190
	v_lshlrev_b32_e32 v190, 16, v191
	v_and_b32_e32 v191, 0xffff0000, v191
	v_lshlrev_b32_e32 v248, 16, v192
	v_and_b32_e32 v249, 0xffff0000, v192
	v_lshlrev_b32_e32 v192, 16, v193
	v_and_b32_e32 v193, 0xffff0000, v193
	v_lshlrev_b32_e32 v250, 16, v194
	v_and_b32_e32 v251, 0xffff0000, v194
	v_lshlrev_b32_e32 v194, 16, v195
	v_and_b32_e32 v195, 0xffff0000, v195
	v_lshlrev_b32_e32 v252, 16, v196
	v_and_b32_e32 v253, 0xffff0000, v196
	v_lshlrev_b32_e32 v196, 16, v197
	v_and_b32_e32 v197, 0xffff0000, v197
	v_pk_fma_f32 v[94:95], v[94:95], v[246:247], v[250:251]
	v_pk_fma_f32 v[96:97], v[96:97], v[190:191], v[194:195]
	v_pk_fma_f32 v[90:91], v[90:91], v[248:249], v[252:253]
	v_pk_fma_f32 v[92:93], v[92:93], v[192:193], v[196:197]
	v_cvt_pk_bf16_f32 v238, v94, v95
	v_cvt_pk_bf16_f32 v239, v96, v97
	v_cvt_pk_bf16_f32 v240, v90, v91
	v_cvt_pk_bf16_f32 v241, v92, v93
	global_store_dwordx4 v244, v[238:241], s[24:25]
	s_waitcnt vmcnt(21)
	v_lshlrev_b32_e32 v246, 16, v198
	v_and_b32_e32 v247, 0xffff0000, v198
	v_lshlrev_b32_e32 v198, 16, v199
	v_and_b32_e32 v199, 0xffff0000, v199
	v_lshlrev_b32_e32 v248, 16, v200
	v_and_b32_e32 v249, 0xffff0000, v200
	v_lshlrev_b32_e32 v200, 16, v201
	v_and_b32_e32 v201, 0xffff0000, v201
	v_lshlrev_b32_e32 v250, 16, v202
	v_and_b32_e32 v251, 0xffff0000, v202
	v_lshlrev_b32_e32 v202, 16, v203
	v_and_b32_e32 v203, 0xffff0000, v203
	v_lshlrev_b32_e32 v252, 16, v204
	v_and_b32_e32 v253, 0xffff0000, v204
	v_lshlrev_b32_e32 v204, 16, v205
	v_and_b32_e32 v205, 0xffff0000, v205
	v_pk_fma_f32 v[86:87], v[86:87], v[246:247], v[250:251]
	v_pk_fma_f32 v[88:89], v[88:89], v[198:199], v[202:203]
	v_pk_fma_f32 v[82:83], v[82:83], v[248:249], v[252:253]
	v_pk_fma_f32 v[84:85], v[84:85], v[200:201], v[204:205]
	v_cvt_pk_bf16_f32 v146, v86, v87
	v_cvt_pk_bf16_f32 v147, v88, v89
	v_cvt_pk_bf16_f32 v148, v82, v83
	v_cvt_pk_bf16_f32 v149, v84, v85
	global_store_dwordx4 v244, v[146:149], s[24:25] offset:256
	v_add_u32_e32 v242, 0x160000, v157
	v_add_u32_e32 v243, 0xb0000, v254
	global_load_dwordx4 v[190:193], v242, s[26:27]
	global_load_dwordx4 v[194:197], v243, s[6:7]
	global_load_dwordx4 v[198:201], v242, s[26:27] offset:256
	global_load_dwordx4 v[202:205], v243, s[6:7] offset:256
	v_add_u32_e32 v244, 0x30000, v254
	s_waitcnt vmcnt(24)
	v_lshlrev_b32_e32 v246, 16, v206
	v_and_b32_e32 v247, 0xffff0000, v206
	v_lshlrev_b32_e32 v206, 16, v207
	v_and_b32_e32 v207, 0xffff0000, v207
	v_lshlrev_b32_e32 v248, 16, v208
	v_and_b32_e32 v249, 0xffff0000, v208
	v_lshlrev_b32_e32 v208, 16, v209
	v_and_b32_e32 v209, 0xffff0000, v209
	v_lshlrev_b32_e32 v250, 16, v210
	v_and_b32_e32 v251, 0xffff0000, v210
	v_lshlrev_b32_e32 v210, 16, v211
	v_and_b32_e32 v211, 0xffff0000, v211
	v_lshlrev_b32_e32 v252, 16, v212
	v_and_b32_e32 v253, 0xffff0000, v212
	v_lshlrev_b32_e32 v212, 16, v213
	v_and_b32_e32 v213, 0xffff0000, v213
	v_pk_fma_f32 v[78:79], v[78:79], v[246:247], v[250:251]
	v_pk_fma_f32 v[80:81], v[80:81], v[206:207], v[210:211]
	v_pk_fma_f32 v[74:75], v[74:75], v[248:249], v[252:253]
	v_pk_fma_f32 v[76:77], v[76:77], v[208:209], v[212:213]
	v_cvt_pk_bf16_f32 v238, v78, v79
	v_cvt_pk_bf16_f32 v239, v80, v81
	v_cvt_pk_bf16_f32 v240, v74, v75
	v_cvt_pk_bf16_f32 v241, v76, v77
	global_store_dwordx4 v244, v[238:241], s[24:25]
	s_waitcnt vmcnt(23)
	v_lshlrev_b32_e32 v246, 16, v214
	v_and_b32_e32 v247, 0xffff0000, v214
	v_lshlrev_b32_e32 v214, 16, v215
	v_and_b32_e32 v215, 0xffff0000, v215
	v_lshlrev_b32_e32 v248, 16, v216
	v_and_b32_e32 v249, 0xffff0000, v216
	v_lshlrev_b32_e32 v216, 16, v217
	v_and_b32_e32 v217, 0xffff0000, v217
	v_lshlrev_b32_e32 v250, 16, v218
	v_and_b32_e32 v251, 0xffff0000, v218
	v_lshlrev_b32_e32 v218, 16, v219
	v_and_b32_e32 v219, 0xffff0000, v219
	v_lshlrev_b32_e32 v252, 16, v220
	v_and_b32_e32 v253, 0xffff0000, v220
	v_lshlrev_b32_e32 v220, 16, v221
	v_and_b32_e32 v221, 0xffff0000, v221
	v_pk_fma_f32 v[70:71], v[70:71], v[246:247], v[250:251]
	v_pk_fma_f32 v[72:73], v[72:73], v[214:215], v[218:219]
	v_pk_fma_f32 v[66:67], v[66:67], v[248:249], v[252:253]
	v_pk_fma_f32 v[68:69], v[68:69], v[216:217], v[220:221]
	v_cvt_pk_bf16_f32 v146, v70, v71
	v_cvt_pk_bf16_f32 v147, v72, v73
	v_cvt_pk_bf16_f32 v148, v66, v67
	v_cvt_pk_bf16_f32 v149, v68, v69
	global_store_dwordx4 v244, v[146:149], s[24:25] offset:256
	v_add_u32_e32 v244, 0x80000, v254
	s_waitcnt vmcnt(22)
	v_lshlrev_b32_e32 v246, 16, v222
	v_and_b32_e32 v247, 0xffff0000, v222
	v_lshlrev_b32_e32 v222, 16, v223
	v_and_b32_e32 v223, 0xffff0000, v223
	v_lshlrev_b32_e32 v248, 16, v224
	v_and_b32_e32 v249, 0xffff0000, v224
	v_lshlrev_b32_e32 v224, 16, v225
	v_and_b32_e32 v225, 0xffff0000, v225
	v_lshlrev_b32_e32 v250, 16, v226
	v_and_b32_e32 v251, 0xffff0000, v226
	v_lshlrev_b32_e32 v226, 16, v227
	v_and_b32_e32 v227, 0xffff0000, v227
	v_lshlrev_b32_e32 v252, 16, v228
	v_and_b32_e32 v253, 0xffff0000, v228
	v_lshlrev_b32_e32 v228, 16, v229
	v_and_b32_e32 v229, 0xffff0000, v229
	v_pk_fma_f32 v[62:63], v[62:63], v[246:247], v[250:251]
	v_pk_fma_f32 v[64:65], v[64:65], v[222:223], v[226:227]
	v_pk_fma_f32 v[58:59], v[58:59], v[248:249], v[252:253]
	v_pk_fma_f32 v[60:61], v[60:61], v[224:225], v[228:229]
	v_cvt_pk_bf16_f32 v238, v62, v63
	v_cvt_pk_bf16_f32 v239, v64, v65
	v_cvt_pk_bf16_f32 v240, v58, v59
	v_cvt_pk_bf16_f32 v241, v60, v61
	global_store_dwordx4 v244, v[238:241], s[24:25]
	s_waitcnt vmcnt(21)
	v_lshlrev_b32_e32 v246, 16, v230
	v_and_b32_e32 v247, 0xffff0000, v230
	v_lshlrev_b32_e32 v230, 16, v231
	v_and_b32_e32 v231, 0xffff0000, v231
	v_lshlrev_b32_e32 v248, 16, v232
	v_and_b32_e32 v249, 0xffff0000, v232
	v_lshlrev_b32_e32 v232, 16, v233
	v_and_b32_e32 v233, 0xffff0000, v233
	v_lshlrev_b32_e32 v250, 16, v234
	v_and_b32_e32 v251, 0xffff0000, v234
	v_lshlrev_b32_e32 v234, 16, v235
	v_and_b32_e32 v235, 0xffff0000, v235
	v_lshlrev_b32_e32 v252, 16, v236
	v_and_b32_e32 v253, 0xffff0000, v236
	v_lshlrev_b32_e32 v236, 16, v237
	v_and_b32_e32 v237, 0xffff0000, v237
	v_pk_fma_f32 v[54:55], v[54:55], v[246:247], v[250:251]
	v_pk_fma_f32 v[56:57], v[56:57], v[230:231], v[234:235]
	v_pk_fma_f32 v[50:51], v[50:51], v[248:249], v[252:253]
	v_pk_fma_f32 v[52:53], v[52:53], v[232:233], v[236:237]
	v_cvt_pk_bf16_f32 v146, v54, v55
	v_cvt_pk_bf16_f32 v147, v56, v57
	v_cvt_pk_bf16_f32 v148, v50, v51
	v_cvt_pk_bf16_f32 v149, v52, v53
	global_store_dwordx4 v244, v[146:149], s[24:25] offset:256
	v_add_u32_e32 v244, 0x90000, v254
	s_waitcnt vmcnt(18)
	v_lshlrev_b32_e32 v246, 16, v158
	v_and_b32_e32 v247, 0xffff0000, v158
	v_lshlrev_b32_e32 v158, 16, v159
	v_and_b32_e32 v159, 0xffff0000, v159
	v_lshlrev_b32_e32 v248, 16, v160
	v_and_b32_e32 v249, 0xffff0000, v160
	v_lshlrev_b32_e32 v160, 16, v161
	v_and_b32_e32 v161, 0xffff0000, v161
	v_lshlrev_b32_e32 v250, 16, v162
	v_and_b32_e32 v251, 0xffff0000, v162
	v_lshlrev_b32_e32 v162, 16, v163
	v_and_b32_e32 v163, 0xffff0000, v163
	v_lshlrev_b32_e32 v252, 16, v164
	v_and_b32_e32 v253, 0xffff0000, v164
	v_lshlrev_b32_e32 v164, 16, v165
	v_and_b32_e32 v165, 0xffff0000, v165
	v_pk_fma_f32 v[46:47], v[46:47], v[246:247], v[250:251]
	v_pk_fma_f32 v[48:49], v[48:49], v[158:159], v[162:163]
	v_pk_fma_f32 v[42:43], v[42:43], v[248:249], v[252:253]
	v_pk_fma_f32 v[44:45], v[44:45], v[160:161], v[164:165]
	v_cvt_pk_bf16_f32 v238, v46, v47
	v_cvt_pk_bf16_f32 v239, v48, v49
	v_cvt_pk_bf16_f32 v240, v42, v43
	v_cvt_pk_bf16_f32 v241, v44, v45
	global_store_dwordx4 v244, v[238:241], s[24:25]
	s_waitcnt vmcnt(17)
	v_lshlrev_b32_e32 v246, 16, v166
	v_and_b32_e32 v247, 0xffff0000, v166
	v_lshlrev_b32_e32 v166, 16, v167
	v_and_b32_e32 v167, 0xffff0000, v167
	v_lshlrev_b32_e32 v248, 16, v168
	v_and_b32_e32 v249, 0xffff0000, v168
	v_lshlrev_b32_e32 v168, 16, v169
	v_and_b32_e32 v169, 0xffff0000, v169
	v_lshlrev_b32_e32 v250, 16, v170
	v_and_b32_e32 v251, 0xffff0000, v170
	v_lshlrev_b32_e32 v170, 16, v171
	v_and_b32_e32 v171, 0xffff0000, v171
	v_lshlrev_b32_e32 v252, 16, v172
	v_and_b32_e32 v253, 0xffff0000, v172
	v_lshlrev_b32_e32 v172, 16, v173
	v_and_b32_e32 v173, 0xffff0000, v173
	v_pk_fma_f32 v[38:39], v[38:39], v[246:247], v[250:251]
	v_pk_fma_f32 v[40:41], v[40:41], v[166:167], v[170:171]
	v_pk_fma_f32 v[34:35], v[34:35], v[248:249], v[252:253]
	v_pk_fma_f32 v[36:37], v[36:37], v[168:169], v[172:173]
	v_cvt_pk_bf16_f32 v146, v38, v39
	v_cvt_pk_bf16_f32 v147, v40, v41
	v_cvt_pk_bf16_f32 v148, v34, v35
	v_cvt_pk_bf16_f32 v149, v36, v37
	global_store_dwordx4 v244, v[146:149], s[24:25] offset:256
	v_add_u32_e32 v244, 0xa0000, v254
	s_waitcnt vmcnt(14)
	v_lshlrev_b32_e32 v246, 16, v174
	v_and_b32_e32 v247, 0xffff0000, v174
	v_lshlrev_b32_e32 v174, 16, v175
	v_and_b32_e32 v175, 0xffff0000, v175
	v_lshlrev_b32_e32 v248, 16, v176
	v_and_b32_e32 v249, 0xffff0000, v176
	v_lshlrev_b32_e32 v176, 16, v177
	v_and_b32_e32 v177, 0xffff0000, v177
	v_lshlrev_b32_e32 v250, 16, v178
	v_and_b32_e32 v251, 0xffff0000, v178
	v_lshlrev_b32_e32 v178, 16, v179
	v_and_b32_e32 v179, 0xffff0000, v179
	v_lshlrev_b32_e32 v252, 16, v180
	v_and_b32_e32 v253, 0xffff0000, v180
	v_lshlrev_b32_e32 v180, 16, v181
	v_and_b32_e32 v181, 0xffff0000, v181
	v_pk_fma_f32 v[30:31], v[30:31], v[246:247], v[250:251]
	v_pk_fma_f32 v[32:33], v[32:33], v[174:175], v[178:179]
	v_pk_fma_f32 v[26:27], v[26:27], v[248:249], v[252:253]
	v_pk_fma_f32 v[28:29], v[28:29], v[176:177], v[180:181]
	v_cvt_pk_bf16_f32 v238, v30, v31
	v_cvt_pk_bf16_f32 v239, v32, v33
	v_cvt_pk_bf16_f32 v240, v26, v27
	v_cvt_pk_bf16_f32 v241, v28, v29
	global_store_dwordx4 v244, v[238:241], s[24:25]
	s_waitcnt vmcnt(13)
	v_lshlrev_b32_e32 v246, 16, v182
	v_and_b32_e32 v247, 0xffff0000, v182
	v_lshlrev_b32_e32 v182, 16, v183
	v_and_b32_e32 v183, 0xffff0000, v183
	v_lshlrev_b32_e32 v248, 16, v184
	v_and_b32_e32 v249, 0xffff0000, v184
	v_lshlrev_b32_e32 v184, 16, v185
	v_and_b32_e32 v185, 0xffff0000, v185
	v_lshlrev_b32_e32 v250, 16, v186
	v_and_b32_e32 v251, 0xffff0000, v186
	v_lshlrev_b32_e32 v186, 16, v187
	v_and_b32_e32 v187, 0xffff0000, v187
	v_lshlrev_b32_e32 v252, 16, v188
	v_and_b32_e32 v253, 0xffff0000, v188
	v_lshlrev_b32_e32 v188, 16, v189
	v_and_b32_e32 v189, 0xffff0000, v189
	v_pk_fma_f32 v[22:23], v[22:23], v[246:247], v[250:251]
	v_pk_fma_f32 v[24:25], v[24:25], v[182:183], v[186:187]
	v_pk_fma_f32 v[18:19], v[18:19], v[248:249], v[252:253]
	v_pk_fma_f32 v[20:21], v[20:21], v[184:185], v[188:189]
	v_cvt_pk_bf16_f32 v146, v22, v23
	v_cvt_pk_bf16_f32 v147, v24, v25
	v_cvt_pk_bf16_f32 v148, v18, v19
	v_cvt_pk_bf16_f32 v149, v20, v21
	global_store_dwordx4 v244, v[146:149], s[24:25] offset:256
	v_add_u32_e32 v244, 0xb0000, v254
	s_waitcnt vmcnt(10)
	v_lshlrev_b32_e32 v246, 16, v190
	v_and_b32_e32 v247, 0xffff0000, v190
	v_lshlrev_b32_e32 v190, 16, v191
	v_and_b32_e32 v191, 0xffff0000, v191
	v_lshlrev_b32_e32 v248, 16, v192
	v_and_b32_e32 v249, 0xffff0000, v192
	v_lshlrev_b32_e32 v192, 16, v193
	v_and_b32_e32 v193, 0xffff0000, v193
	v_lshlrev_b32_e32 v250, 16, v194
	v_and_b32_e32 v251, 0xffff0000, v194
	v_lshlrev_b32_e32 v194, 16, v195
	v_and_b32_e32 v195, 0xffff0000, v195
	v_lshlrev_b32_e32 v252, 16, v196
	v_and_b32_e32 v253, 0xffff0000, v196
	v_lshlrev_b32_e32 v196, 16, v197
	v_and_b32_e32 v197, 0xffff0000, v197
	v_pk_fma_f32 v[14:15], v[14:15], v[246:247], v[250:251]
	v_pk_fma_f32 v[16:17], v[16:17], v[190:191], v[194:195]
	v_pk_fma_f32 v[10:11], v[10:11], v[248:249], v[252:253]
	v_pk_fma_f32 v[12:13], v[12:13], v[192:193], v[196:197]
	v_cvt_pk_bf16_f32 v238, v14, v15
	v_cvt_pk_bf16_f32 v239, v16, v17
	v_cvt_pk_bf16_f32 v240, v10, v11
	v_cvt_pk_bf16_f32 v241, v12, v13
	global_store_dwordx4 v244, v[238:241], s[24:25]
	s_waitcnt vmcnt(9)
	v_lshlrev_b32_e32 v246, 16, v198
	v_and_b32_e32 v247, 0xffff0000, v198
	v_lshlrev_b32_e32 v198, 16, v199
	v_and_b32_e32 v199, 0xffff0000, v199
	v_lshlrev_b32_e32 v248, 16, v200
	v_and_b32_e32 v249, 0xffff0000, v200
	v_lshlrev_b32_e32 v200, 16, v201
	v_and_b32_e32 v201, 0xffff0000, v201
	v_lshlrev_b32_e32 v250, 16, v202
	v_and_b32_e32 v251, 0xffff0000, v202
	v_lshlrev_b32_e32 v202, 16, v203
	v_and_b32_e32 v203, 0xffff0000, v203
	v_lshlrev_b32_e32 v252, 16, v204
	v_and_b32_e32 v253, 0xffff0000, v204
	v_lshlrev_b32_e32 v204, 16, v205
	v_and_b32_e32 v205, 0xffff0000, v205
	v_pk_fma_f32 v[6:7], v[6:7], v[246:247], v[250:251]
	v_pk_fma_f32 v[8:9], v[8:9], v[198:199], v[202:203]
	v_pk_fma_f32 v[2:3], v[2:3], v[248:249], v[252:253]
	v_pk_fma_f32 v[4:5], v[4:5], v[200:201], v[204:205]
	v_cvt_pk_bf16_f32 v146, v6, v7
	v_cvt_pk_bf16_f32 v147, v8, v9
	v_cvt_pk_bf16_f32 v148, v2, v3
	v_cvt_pk_bf16_f32 v149, v4, v5
	global_store_dwordx4 v244, v[146:149], s[24:25] offset:256
	s_cbranch_vccnz .LBB0_548
	s_andn2_b64 vcc, exec, s[2:3]
	s_cbranch_vccnz .LBB0_547
	s_barrier
	s_branch .LBB0_547

	.amdhsa_kernel _Z6mk_fwd4Args
		.amdhsa_group_segment_fixed_size 0
		.amdhsa_private_segment_fixed_size 0
		.amdhsa_kernarg_size 544
		.amdhsa_user_sgpr_count 2
		.amdhsa_user_sgpr_dispatch_ptr 0
		.amdhsa_user_sgpr_queue_ptr 0
		.amdhsa_user_sgpr_kernarg_segment_ptr 1
		.amdhsa_user_sgpr_dispatch_id 0
		.amdhsa_user_sgpr_kernarg_preload_length 0
		.amdhsa_user_sgpr_kernarg_preload_offset 0
		.amdhsa_user_sgpr_private_segment_size 0
		.amdhsa_uses_dynamic_stack 0
		.amdhsa_enable_private_segment 0
		.amdhsa_system_sgpr_workgroup_id_x 1
		.amdhsa_system_sgpr_workgroup_id_y 0
		.amdhsa_system_sgpr_workgroup_id_z 0
		.amdhsa_system_sgpr_workgroup_info 0
		.amdhsa_system_vgpr_workitem_id 0
		.amdhsa_next_free_vgpr 256
		.amdhsa_next_free_sgpr 102
		.amdhsa_accum_offset 256
		.amdhsa_reserve_vcc 1
		.amdhsa_float_round_mode_32 0
		.amdhsa_float_round_mode_16_64 0
		.amdhsa_float_denorm_mode_32 3
		.amdhsa_float_denorm_mode_16_64 3
		.amdhsa_dx10_clamp 1
		.amdhsa_ieee_mode 1
		.amdhsa_fp16_overflow 0
		.amdhsa_tg_split 0
		.amdhsa_exception_fp_ieee_invalid_op 0
		.amdhsa_exception_fp_denorm_src 0
		.amdhsa_exception_fp_ieee_div_zero 0
		.amdhsa_exception_fp_ieee_overflow 0
		.amdhsa_exception_fp_ieee_underflow 0
		.amdhsa_exception_fp_ieee_inexact 0
		.amdhsa_exception_int_div_zero 0
	.end_amdhsa_kernel

amdhsa.kernels:
  - .agpr_count:     0
    .args:
      - .offset:         0
        .size:           288
        .value_kind:     by_value
      - .offset:         288
        .size:           4
        .value_kind:     hidden_block_count_x
      - .offset:         292
        .size:           4
        .value_kind:     hidden_block_count_y
      - .offset:         296
        .size:           4
        .value_kind:     hidden_block_count_z
      - .offset:         300
        .size:           2
        .value_kind:     hidden_group_size_x
      - .offset:         302
        .size:           2
        .value_kind:     hidden_group_size_y
      - .offset:         304
        .size:           2
        .value_kind:     hidden_group_size_z
      - .offset:         306
        .size:           2
        .value_kind:     hidden_remainder_x
      - .offset:         308
        .size:           2
        .value_kind:     hidden_remainder_y
      - .offset:         310
        .size:           2
        .value_kind:     hidden_remainder_z
      - .offset:         328
        .size:           8
        .value_kind:     hidden_global_offset_x
      - .offset:         336
        .size:           8
        .value_kind:     hidden_global_offset_y
      - .offset:         344
        .size:           8
        .value_kind:     hidden_global_offset_z
      - .offset:         352
        .size:           2
        .value_kind:     hidden_grid_dims
      - .offset:         376
        .size:           8
        .value_kind:     hidden_multigrid_sync_arg
      - .offset:         408
        .size:           4
        .value_kind:     hidden_dynamic_lds_size
    .group_segment_fixed_size: 0
    .kernarg_segment_align: 8
    .kernarg_segment_size: 544
    .language:       OpenCL C
    .language_version:
      - 2
      - 0
    .max_flat_workgroup_size: 512
    .name:           _Z6mk_fwd4Args
    .private_segment_fixed_size: 0
    .sgpr_count:     108
    .sgpr_spill_count: 162
    .symbol:         _Z6mk_fwd4Args.kd
    .uniform_work_group_size: 1
    .uses_dynamic_stack: false
    .vgpr_count:     256
    .vgpr_spill_count: 0
    .wavefront_size: 64
